# LN1 row loop: wait for the prefetched next row moved from the loop top to its first consumer (the register copies), vmcnt(4)
# baseline (speedup 1.0000x reference)
; __device__ __forceinline__ void ln_phase(float* buf, float* stats, const float* g, const float* b, bf16_t* xb, int wid, int lane) {
;     ...
;     f32x4 v[8], nx[8], gg[8], bb[8];
;     ...
; #pragma unroll
;     for (int k = 0; k < 8; ++k) { gg[k] = ((const f32x4*)g)[LN_IDX(k)]; bb[k] = ((const f32x4*)b)[LN_IDX(k)]; }
;     if (gw < NTOK) {
; #pragma unroll
;         for (int k = 0; k < 8; ++k) v[k] = ((const f32x4*)(buf + (size_t)gw * DM))[LN_IDX(k)];
;     }
;     for (int row = gw; row < NTOK; row += NGW) {
.LBB0_601:
	s_or_b64 exec, exec, s[0:1]
	s_waitcnt lgkmcnt(0)
	s_barrier
	v_mbcnt_lo_u32_b32 v0, -1, 0
	v_mbcnt_hi_u32_b32 v0, -1, v0
	v_readlane_b32 s2, v254, 55
	v_add_u32_e32 v0, s61, v0
	v_readlane_b32 s40, v252, 2
	s_lshl_b32 s76, s2, 11
	v_readfirstlane_b32 s0, v0
	v_readlane_b32 s52, v252, 14
	v_readlane_b32 s53, v252, 15
	s_ashr_i32 s0, s0, 6
	s_lshl_b64 s[80:81], s[76:77], 2
	v_readlane_b32 s54, v252, 16
	v_readlane_b32 s55, v252, 17
	s_mov_b64 s[16:17], s[52:53]
	s_add_u32 s82, s16, s80
	s_mov_b64 s[18:19], s[54:55]
	s_addc_u32 s83, s17, s81
	v_readlane_b32 s48, v252, 10
	v_readlane_b32 s49, v252, 11
	v_readlane_b32 s50, v252, 12
	v_readlane_b32 s51, v252, 13
	s_add_u32 s84, s18, s80
	v_readlane_b32 s1, v252, 31
	s_addc_u32 s85, s19, s81
	s_add_i32 s2, s0, s1
	v_readlane_b32 s10, v255, 6
	v_readlane_b32 s48, v255, 10
	v_readlane_b32 s50, v255, 12
	s_cmpk_gt_i32 s2, 0x7fff
	v_readlane_b32 s11, v255, 7
	v_readlane_b32 s49, v255, 11
	v_readlane_b32 s51, v255, 13
	v_readlane_b32 s54, v255, 15
	v_readlane_b32 s3, v254, 56
	v_readlane_b32 s41, v252, 3
	v_readlane_b32 s42, v252, 4
	v_readlane_b32 s43, v252, 5
	v_readlane_b32 s44, v252, 6
	v_readlane_b32 s45, v252, 7
	v_readlane_b32 s46, v252, 8
	v_readlane_b32 s47, v252, 9
	v_readlane_b32 s55, v255, 16
	s_cbranch_scc1 .LBB0_608
	s_waitcnt vmcnt(8)
	v_and_b32_e32 v126, 63, v0
	v_lshlrev_b32_e32 v0, 5, v126
	global_load_dwordx4 v[2:5], v0, s[82:83] offset:16
	global_load_dwordx4 v[6:9], v0, s[82:83]
	global_load_dwordx4 v[10:13], v0, s[84:85] offset:16
	global_load_dwordx4 v[14:17], v0, s[84:85]
	global_load_dwordx4 v[18:21], v0, s[82:83] offset:2064
	global_load_dwordx4 v[22:25], v0, s[82:83] offset:2048
	global_load_dwordx4 v[26:29], v0, s[84:85] offset:2064
	global_load_dwordx4 v[30:33], v0, s[84:85] offset:2048
	s_ashr_i32 s3, s2, 31
	s_lshl_b64 s[4:5], s[2:3], 13
	s_add_u32 s4, s72, s4
	s_addc_u32 s5, s73, s5
	v_or_b32_e32 v58, 0x1000, v0
	global_load_dwordx4 v[118:121], v0, s[4:5]
	global_load_dwordx4 v[130:133], v0, s[4:5] offset:16
	global_load_dwordx4 v[34:37], v58, s[82:83] offset:16
	global_load_dwordx4 v[38:41], v58, s[82:83]
	global_load_dwordx4 v[42:45], v58, s[84:85] offset:16
	global_load_dwordx4 v[46:49], v58, s[84:85]
	global_load_dwordx4 v[114:117], v0, s[4:5] offset:2048
	v_or_b32_e32 v62, 0x1800, v0
	global_load_dwordx4 v[106:109], v58, s[4:5]
	global_load_dwordx4 v[50:53], v62, s[82:83] offset:16
	global_load_dwordx4 v[54:57], v62, s[82:83]
	global_load_dwordx4 v[110:113], v58, s[4:5] offset:16
	global_load_dwordx4 v[102:105], v62, s[4:5]
	global_load_dwordx4 v[98:101], v62, s[4:5] offset:16
	s_nop 0
	global_load_dwordx4 v[58:61], v62, s[84:85] offset:16
	s_nop 0
	global_load_dwordx4 v[62:65], v62, s[84:85]
	s_nop 0
	global_load_dwordx4 v[122:125], v0, s[4:5] offset:2064
	s_lshl_b64 s[4:5], s[2:3], 3
	s_lshl_b32 s1, s34, 2
	s_add_u32 s1, s4, s1
	s_addc_u32 s4, s5, 0
	s_add_u32 s6, s1, 0xc000000
	v_readlane_b32 s1, v254, 50
	s_addc_u32 s7, s4, 0
	s_add_i32 s0, s1, s0
	s_ashr_i32 s1, s0, 31
	s_lshl_b64 s[4:5], s[2:3], 12
	s_lshl_b64 s[0:1], s[0:1], 13
	v_readlane_b32 s3, v254, 48
	s_add_u32 s0, s3, s0
	v_readlane_b32 s3, v254, 49
	s_addc_u32 s1, s3, s1
	v_cmp_eq_u32_e64 s[40:41], 0, v126
	v_lshl_or_b32 v126, v126, 4, s4
	v_mov_b32_e32 v127, s5
	v_lshl_add_u64 v[128:129], s[0:1], 0, v[0:1]
	s_waitcnt vmcnt(8)
	v_mov_b32_e32 v138, v107
	v_mov_b32_e32 v135, v118
	v_mov_b32_e32 v137, v120
	v_mov_b32_e32 v134, v130
	v_mov_b32_e32 v118, v131
	v_mov_b32_e32 v136, v132
	v_mov_b32_e32 v120, v133
	v_mov_b32_e32 v132, v115
	v_mov_b32_e32 v133, v116
	v_mov_b32_e32 v115, v117
	v_mov_b32_e32 v130, v109
	s_waitcnt vmcnt(5)
	v_mov_b32_e32 v116, v111
	v_mov_b32_e32 v117, v112
	v_mov_b32_e32 v111, v113
	s_waitcnt vmcnt(3)
	v_mov_b32_e32 v140, v99
	v_mov_b32_e32 v112, v101
	s_waitcnt vmcnt(0)
	s_branch .LBB0_604
; __device__ __forceinline__ unsigned cvt_pk_bf16(float lo, float hi) { const f32x2_t v = {lo, hi}; const bf16x2_t b = __builtin_convertvector(v, bf16x2_t); return __builtin_bit_cast(unsigned, b); }
; __device__ __forceinline__ void ln_phase(float* buf, float* stats, const float* g, const float* b, bf16_t* xb, int wid, int lane) {
;     ...
;         for (int q = 0; q < 4; ++q) { const f32x4 y0 = (v[2 * q] * rstd) * gg[2 * q] + bb[2 * q], y1 = (v[2 * q + 1] * rstd) * gg[2 * q + 1] + bb[2 * q + 1];
;             if (!stats) { rp[LN_IDX(2 * q)] = y0; rp[LN_IDX(2 * q + 1)] = y1; }
;             if (xb) { u32x4 w; w.x = cvt_pk_bf16(y0[0], y0[1]); w.y = cvt_pk_bf16(y0[2], y0[3]); w.z = cvt_pk_bf16(y1[0], y1[1]); w.w = cvt_pk_bf16(y1[2], y1[3]); *((u32x4*)(xb + (size_t)row * DM) + lane + 64 * q) = w; } }
; #pragma unroll
;         for (int k = 0; k < 8; ++k) v[k] = nx[k];
.LBB0_603:
	s_or_b64 exec, exec, s[0:1]
	v_mov_b32_e32 v142, v135
	v_mov_b32_e32 v143, v119
	v_mov_b32_e32 v135, v118
	v_mov_b32_e32 v118, v137
	v_mov_b32_e32 v119, v121
	v_mov_b32_e32 v137, v120
	v_mov_b32_e32 v99, v140
	v_lshl_add_u64 v[140:141], s[74:75], 0, v[126:127]
	v_pk_mul_f32 v[118:119], v[118:119], v[0:1] op_sel_hi:[1,0]
	v_pk_mul_f32 v[142:143], v[142:143], v[0:1] op_sel_hi:[1,0]
	v_pk_mul_f32 v[120:121], v[136:137], v[0:1] op_sel_hi:[1,0]
	v_pk_mul_f32 v[134:135], v[134:135], v[0:1] op_sel_hi:[1,0]
	s_mov_b32 s0, 0xc200000
	v_pk_fma_f32 v[146:147], v[8:9], v[118:119], v[16:17]
	v_pk_fma_f32 v[118:119], v[6:7], v[142:143], v[14:15]
	v_pk_fma_f32 v[136:137], v[4:5], v[120:121], v[12:13]
	v_pk_fma_f32 v[120:121], v[2:3], v[134:135], v[10:11]
	v_add_co_u32_e32 v134, vcc, s0, v140
	v_mov_b32_e32 v144, v114
	v_mov_b32_e32 v145, v132
	v_cvt_pk_bf16_f32 v118, v118, v119
	v_cvt_pk_bf16_f32 v119, v146, v147
	v_cvt_pk_bf16_f32 v120, v120, v121
	v_cvt_pk_bf16_f32 v121, v136, v137
	v_addc_co_u32_e32 v135, vcc, 0, v141, vcc
	v_mov_b32_e32 v114, v133
	global_store_dwordx4 v[134:135], v[118:121], off
	v_pk_mul_f32 v[114:115], v[114:115], v[0:1] op_sel_hi:[1,0]
	v_mov_b32_e32 v107, v138
	v_pk_mul_f32 v[118:119], v[144:145], v[0:1] op_sel_hi:[1,0]
	v_mov_b32_e32 v138, v110
	v_mov_b32_e32 v139, v116
	v_pk_fma_f32 v[114:115], v[24:25], v[114:115], v[32:33]
	v_pk_fma_f32 v[118:119], v[22:23], v[118:119], v[30:31]
	v_mov_b32_e32 v109, v130
	v_mov_b32_e32 v110, v117
	v_readlane_b32 s0, v254, 44
	v_cvt_pk_bf16_f32 v118, v118, v119
	v_cvt_pk_bf16_f32 v119, v114, v115
	v_pk_mul_f32 v[108:109], v[108:109], v[0:1] op_sel_hi:[1,0]
	v_pk_mul_f32 v[106:107], v[106:107], v[0:1] op_sel_hi:[1,0]
	v_pk_mul_f32 v[110:111], v[110:111], v[0:1] op_sel_hi:[1,0]
	v_pk_mul_f32 v[114:115], v[138:139], v[0:1] op_sel_hi:[1,0]
	v_readlane_b32 s1, v254, 45
	s_add_u32 s6, s6, s0
	v_pk_fma_f32 v[108:109], v[40:41], v[108:109], v[48:49]
	v_pk_fma_f32 v[106:107], v[38:39], v[106:107], v[46:47]
	v_pk_fma_f32 v[110:111], v[36:37], v[110:111], v[44:45]
	v_pk_fma_f32 v[114:115], v[34:35], v[114:115], v[42:43]
	v_mov_b32_e32 v101, v112
	s_addc_u32 s7, s7, s1
	v_readlane_b32 s0, v254, 46
	v_pk_mul_f32 v[120:121], v[124:125], v[0:1] op_sel_hi:[1,0]
	v_pk_mul_f32 v[122:123], v[122:123], v[0:1] op_sel_hi:[1,0]
	v_cvt_pk_bf16_f32 v106, v106, v107
	v_cvt_pk_bf16_f32 v107, v108, v109
	v_cvt_pk_bf16_f32 v108, v114, v115
	v_cvt_pk_bf16_f32 v109, v110, v111
	v_pk_mul_f32 v[104:105], v[104:105], v[0:1] op_sel_hi:[1,0]
	v_pk_mul_f32 v[102:103], v[102:103], v[0:1] op_sel_hi:[1,0]
	v_pk_mul_f32 v[100:101], v[100:101], v[0:1] op_sel_hi:[1,0]
	v_pk_mul_f32 v[98:99], v[98:99], v[0:1] op_sel_hi:[1,0]
	v_readlane_b32 s1, v254, 47
	v_pk_fma_f32 v[124:125], v[20:21], v[120:121], v[28:29]
	v_pk_fma_f32 v[120:121], v[18:19], v[122:123], v[26:27]
	global_store_dwordx4 v[134:135], v[106:109], off offset:2048
	v_pk_fma_f32 v[104:105], v[56:57], v[104:105], v[64:65]
	v_pk_fma_f32 v[102:103], v[54:55], v[102:103], v[62:63]
	v_pk_fma_f32 v[106:107], v[52:53], v[100:101], v[60:61]
	v_pk_fma_f32 v[100:101], v[50:51], v[98:99], v[58:59]
	v_lshl_add_u64 v[126:127], v[126:127], 0, s[0:1]
	v_readlane_b32 s0, v254, 53
	v_cvt_pk_bf16_f32 v120, v120, v121
	v_cvt_pk_bf16_f32 v121, v124, v125
	v_cvt_pk_bf16_f32 v98, v102, v103
	v_cvt_pk_bf16_f32 v99, v104, v105
	v_cvt_pk_bf16_f32 v100, v100, v101
	v_cvt_pk_bf16_f32 v101, v106, v107
	v_readlane_b32 s1, v254, 54
	global_store_dwordx4 v[134:135], v[118:121], off offset:1024
	global_store_dwordx4 v[134:135], v[98:101], off offset:3072
	v_lshl_add_u64 v[128:129], v[128:129], 0, s[0:1]
	s_andn2_b64 vcc, exec, s[4:5]
	s_waitcnt vmcnt(4)
	v_mov_b32_e32 v135, v66
	v_mov_b32_e32 v119, v67
	v_mov_b32_e32 v137, v68
	v_mov_b32_e32 v121, v69
	v_mov_b32_e32 v134, v70
	v_mov_b32_e32 v118, v71
	v_mov_b32_e32 v136, v72
	v_mov_b32_e32 v120, v73
	v_mov_b32_e32 v114, v74
	v_mov_b32_e32 v132, v75
	v_mov_b32_e32 v133, v76
	v_mov_b32_e32 v115, v77
	v_mov_b32_e32 v122, v78
	v_mov_b32_e32 v123, v79
	v_mov_b32_e32 v124, v80
	v_mov_b32_e32 v125, v81
	v_mov_b32_e32 v106, v82
	v_mov_b32_e32 v138, v83
	v_mov_b32_e32 v108, v84
	v_mov_b32_e32 v130, v85
	v_mov_b32_e32 v110, v86
	v_mov_b32_e32 v116, v87
	v_mov_b32_e32 v117, v88
	v_mov_b32_e32 v111, v89
	v_mov_b32_e32 v102, v90
	v_mov_b32_e32 v103, v91
	v_mov_b32_e32 v104, v92
	v_mov_b32_e32 v105, v93
	v_mov_b32_e32 v98, v94
	v_mov_b32_e32 v140, v95
	v_mov_b32_e32 v100, v96
	v_mov_b32_e32 v112, v97
	s_cbranch_vccz .LBB0_608

; __device__ __forceinline__ void ln_phase(float* buf, float* stats, const float* g, const float* b, bf16_t* xb, int wid, int lane) {
;     ...
;         float s = 0.f;
; #pragma unroll
;         for (int k = 0; k < 8; ++k) s += (v[k][0] + v[k][1]) + (v[k][2] + v[k][3]);
;         const float mean = wave_sum(s, lane) * (1.f / DM); float s2 = 0.f;
; #pragma unroll
;         for (int k = 0; k < 8; ++k) { v[k] = v[k] - mean; s2 += (v[k][0] * v[k][0] + v[k][1] * v[k][1]) + (v[k][2] * v[k][2] + v[k][3] * v[k][3]); }
;         const float rstd = 1.f / sqrtf(wave_sum(s2, lane) * (1.f / DM) + 1e-5f);
;         if (stats && lane == 0) { f32x2_t t = {mean, rstd}; *(f32x2_t*)(stats + 2 * (size_t)row) = t; }
.LBB0_606:
	v_pk_add_f32 v[142:143], v[134:135], v[118:119]
	v_pk_add_f32 v[144:145], v[136:137], v[120:121]
	v_add_f32_e32 v107, v122, v123
	v_pk_add_f32 v[142:143], v[142:143], v[144:145]
	v_add_f32_e32 v139, v124, v125
	v_add_f32_e32 v0, 0, v143
	v_add_f32_e32 v131, v142, v0
	v_pk_add_f32 v[142:143], v[132:133], v[114:115]
	v_pk_add_f32 v[144:145], v[106:107], v[138:139]
	v_pk_add_f32 v[142:143], v[142:143], v[142:143] op_sel_hi:[0,1]
	v_mov_b32_e32 v109, v143
	v_pk_add_f32 v[142:143], v[108:109], v[130:131]
	v_add_f32_e32 v99, v102, v103
	v_pk_add_f32 v[142:143], v[144:145], v[142:143]
	v_pk_add_f32 v[144:145], v[116:117], v[110:111]
	v_pk_add_f32 v[142:143], v[142:143], v[142:143] op_sel_hi:[0,1]
	v_pk_add_f32 v[144:145], v[144:145], v[144:145] op_sel_hi:[0,1]
	v_add_f32_e32 v141, v104, v105
	v_mov_b32_e32 v101, v145
	v_mov_b32_e32 v113, v143
	v_pk_add_f32 v[146:147], v[98:99], v[140:141]
	v_pk_add_f32 v[142:143], v[100:101], v[112:113]
	s_nop 0
	v_pk_add_f32 v[142:143], v[146:147], v[142:143]
	s_nop 0
	v_add_f32_e32 v0, v142, v143
	s_nop 1
	v_add_f32_dpp v0, v0, v0 row_ror:8 row_mask:0xf bank_mask:0xf bound_ctrl:1
	s_nop 1
	v_add_f32_dpp v0, v0, v0 row_ror:4 row_mask:0xf bank_mask:0xf bound_ctrl:1
	s_nop 1
	v_add_f32_dpp v0, v0, v0 row_ror:2 row_mask:0xf bank_mask:0xf bound_ctrl:1
	s_nop 1
	v_add_f32_dpp v0, v0, v0 row_ror:1 row_mask:0xf bank_mask:0xf bound_ctrl:1
	s_nop 0
	v_readlane_b32 s3, v0, 16
	v_readlane_b32 s8, v0, 48
	v_readlane_b32 s0, v0, 0
	v_readlane_b32 s1, v0, 32
	v_mov_b32_e32 v142, s3
	v_mov_b32_e32 v143, s8
	v_pk_add_f32 v[142:143], s[0:1], v[142:143]
	s_nop 0
	v_add_f32_e32 v99, v142, v143
	v_fmac_f32_e32 v121, 0xba000000, v99
	v_fmac_f32_e32 v119, 0xba000000, v99
	v_fmac_f32_e32 v137, 0xba000000, v99
	v_fmac_f32_e32 v135, 0xba000000, v99
	v_mul_f32_e32 v0, v119, v119
	v_mul_f32_e32 v101, v121, v121
	v_fmac_f32_e32 v0, v135, v135
	v_fmac_f32_e32 v101, v137, v137
	v_fmac_f32_e32 v120, 0xba000000, v99
	v_fmac_f32_e32 v118, 0xba000000, v99
	v_add_f32_e32 v0, v0, v101
	v_fmac_f32_e32 v136, 0xba000000, v99
	v_fmac_f32_e32 v134, 0xba000000, v99
	v_mul_f32_e32 v101, v118, v118
	v_mul_f32_e32 v107, v120, v120
	v_fmac_f32_e32 v101, v134, v134
	v_fmac_f32_e32 v107, v136, v136
	v_add_f32_e32 v101, v101, v107
	v_fmac_f32_e32 v115, 0xba000000, v99
	v_fmac_f32_e32 v132, 0xba000000, v99
	v_add_f32_e32 v0, v0, v101
	v_fmac_f32_e32 v133, 0xba000000, v99
	v_fmac_f32_e32 v114, 0xba000000, v99
	v_mul_f32_e32 v101, v132, v132
	v_mul_f32_e32 v107, v115, v115
	v_fmac_f32_e32 v101, v114, v114
	v_fmac_f32_e32 v107, v133, v133
	v_add_f32_e32 v101, v101, v107
	v_fmac_f32_e32 v125, 0xba000000, v99
	v_fmac_f32_e32 v123, 0xba000000, v99
	v_add_f32_e32 v0, v101, v0
	v_fmac_f32_e32 v124, 0xba000000, v99
	v_fmac_f32_e32 v122, 0xba000000, v99
	v_mul_f32_e32 v101, v123, v123
	v_mul_f32_e32 v107, v125, v125
	v_fmac_f32_e32 v101, v122, v122
	v_fmac_f32_e32 v107, v124, v124
	v_add_f32_e32 v101, v101, v107
	v_fmac_f32_e32 v130, 0xba000000, v99
	v_fmac_f32_e32 v138, 0xba000000, v99
	v_add_f32_e32 v0, v101, v0
	v_fmac_f32_e32 v108, 0xba000000, v99
	v_fmac_f32_e32 v106, 0xba000000, v99
	v_mul_f32_e32 v101, v138, v138
	v_mul_f32_e32 v107, v130, v130
	v_fmac_f32_e32 v101, v106, v106
	v_fmac_f32_e32 v107, v108, v108
	v_add_f32_e32 v101, v101, v107
	v_fmac_f32_e32 v111, 0xba000000, v99
	v_fmac_f32_e32 v116, 0xba000000, v99
	v_add_f32_e32 v0, v101, v0
	v_fmac_f32_e32 v117, 0xba000000, v99
	v_fmac_f32_e32 v110, 0xba000000, v99
	v_mul_f32_e32 v101, v116, v116
	v_mul_f32_e32 v107, v111, v111
	v_fmac_f32_e32 v101, v110, v110
	v_fmac_f32_e32 v107, v117, v117
	v_add_f32_e32 v101, v101, v107
	v_fmac_f32_e32 v105, 0xba000000, v99
	v_fmac_f32_e32 v103, 0xba000000, v99
	v_add_f32_e32 v0, v101, v0
	v_fmac_f32_e32 v104, 0xba000000, v99
	v_fmac_f32_e32 v102, 0xba000000, v99
	v_mul_f32_e32 v101, v103, v103
	v_mul_f32_e32 v107, v105, v105
	v_fmac_f32_e32 v101, v102, v102
	v_fmac_f32_e32 v107, v104, v104
	v_add_f32_e32 v101, v101, v107
	v_fmac_f32_e32 v112, 0xba000000, v99
	v_fmac_f32_e32 v140, 0xba000000, v99
	v_add_f32_e32 v0, v101, v0
	v_fmac_f32_e32 v100, 0xba000000, v99
	v_fmac_f32_e32 v98, 0xba000000, v99
	v_mul_f32_e32 v101, v140, v140
	v_mul_f32_e32 v107, v112, v112
	v_fmac_f32_e32 v101, v98, v98
	v_fmac_f32_e32 v107, v100, v100
	v_add_f32_e32 v101, v101, v107
	v_add_f32_e32 v0, v101, v0
	s_nop 1
	v_add_f32_dpp v0, v0, v0 row_ror:8 row_mask:0xf bank_mask:0xf bound_ctrl:1
	s_nop 1
	v_add_f32_dpp v0, v0, v0 row_ror:4 row_mask:0xf bank_mask:0xf bound_ctrl:1
	s_nop 1
	v_add_f32_dpp v0, v0, v0 row_ror:2 row_mask:0xf bank_mask:0xf bound_ctrl:1
	s_nop 1
	v_add_f32_dpp v0, v0, v0 row_ror:1 row_mask:0xf bank_mask:0xf bound_ctrl:1
	s_nop 0
	v_readlane_b32 s1, v0, 16
	v_readlane_b32 s8, v0, 48
	v_readlane_b32 s0, v0, 0
	v_readlane_b32 s3, v0, 32
	v_mov_b32_e32 v0, s1
	v_mov_b32_e32 v101, s8
	v_add_f32_e32 v0, s0, v0
	v_add_f32_e32 v101, s3, v101
	v_add_f32_e32 v0, v0, v101
	v_fmamk_f32 v0, v0, 0x3a000000, v226
	s_mov_b32 s0, 0xf800000
	v_mul_f32_e32 v101, 0x4f800000, v0
	v_cmp_gt_f32_e32 vcc, s0, v0
	s_nop 1
	v_cndmask_b32_e32 v0, v0, v101, vcc
	v_sqrt_f32_e32 v101, v0
	s_nop 0
	v_add_u32_e32 v107, -1, v101
	v_fma_f32 v109, -v107, v101, v0
	v_cmp_ge_f32_e64 s[0:1], 0, v109
	v_add_u32_e32 v109, 1, v101
	s_nop 0
	v_cndmask_b32_e64 v107, v101, v107, s[0:1]
	v_fma_f32 v101, -v109, v101, v0
	v_cmp_lt_f32_e64 s[0:1], 0, v101
	s_nop 1
	v_cndmask_b32_e64 v101, v107, v109, s[0:1]
	v_mul_f32_e32 v107, 0x37800000, v101
	v_cndmask_b32_e32 v101, v101, v107, vcc
	v_cmp_class_f32_e32 vcc, v0, v224
	s_nop 1
	v_cndmask_b32_e32 v0, v101, v0, vcc
	v_div_scale_f32 v101, s[0:1], v0, v0, 1.0
	v_rcp_f32_e32 v107, v101
	s_nop 0
	v_fma_f32 v109, -v101, v107, 1.0
	v_fmac_f32_e32 v107, v109, v107
	v_div_scale_f32 v109, vcc, 1.0, v0, 1.0
	v_mul_f32_e32 v113, v109, v107
	v_fma_f32 v131, -v101, v113, v109
	v_fmac_f32_e32 v113, v131, v107
	v_fma_f32 v101, -v101, v113, v109
	v_div_fmas_f32 v101, v101, v107, v113
	v_div_fixup_f32 v0, v101, v0, 1.0
	s_and_saveexec_b64 s[0:1], s[40:41]
	s_cbranch_execz .LBB0_603
	s_add_u32 s8, s74, s6
	v_mul_f32_e32 v142, 0x3a000000, v99
	s_addc_u32 s9, s75, s7
	v_mov_b32_e32 v143, v0
	global_store_dwordx2 v1, v[142:143], s[8:9]
	s_branch .LBB0_603
